# merge phase rewritten by hand: 128x128 tiles on the LDS-DMA K-loop (was 64x128), packed 8-byte epilogue stores via swapped MFMA operands
# speedup vs baseline: 1.1420x; 1.1420x over previous
; DI unsigned pack2(float a, float b) { f32v2 v = {a, b}; return __builtin_bit_cast(unsigned, __builtin_convertvector(v, bf16v2)); }
; DI float sigm_fast(float x) { return __builtin_amdgcn_rcpf(1.f + __expf(-x)); }
; DI int fetch_item(unsigned* ctr, char* smem) {
;   volatile int* slot = (volatile int*)(smem + SMEM_BYTES - 16);
;   __syncthreads();
;   if (threadIdx.x == 0) *slot = (int)__hip_atomic_fetch_add(ctr, 1u, __ATOMIC_RELAXED, __HIP_MEMORY_SCOPE_AGENT);
;   __syncthreads();
;   return *slot;
; DI void phase_merge(const Params& p, int l, char* smem, int tid) {
;   const int lane = tid & 63, w = tid >> 6, r = lane & 31, h = lane >> 5, wm = w >> 1, wn = w & 1;
;   GemmLds* s = (GemmLds*)smem;
;   u16* ACC = p.Pk;
;   const bool dyn = (l == 0);
;   unsigned* qc = p.bar + 4096 + 320;
;   for (int it = (dyn ? fetch_item(qc, smem) : (int)blockIdx.x); it < 544 * 8; it = (dyn ? fetch_item(qc, smem) : it + (int)gridDim.x)) {
;     const int mt = it >> 3, nt = it & 7, m0 = mt * 64, n0 = nt * 128;
;     if (l == 1 && (mt % 68) < 4) continue;
;     f32x16 accT[1][2]; zero_acc<1>(accT);
; #pragma unroll 1
;     for (int i = 0; i < 4; i++) {
;       if ((ZERO_MASK >> i) & 1) continue;
;       unsigned sg[2][8];
;       {
;         f32x16 m[1][2]; zero_acc<1>(m);
;         gemm_main<1>(p.xn + (size_t)m0 * 1024, 1024, p.WtM + (size_t)l * 4096 * 1024 + ((size_t)i * 1024 + n0) * 1024, 1024, 1024, m, s, tid);
; #pragma unroll
;         for (int b2 = 0; b2 < 2; b2++)
; #pragma unroll
;           for (int e = 0; e < 8; e++) sg[b2][e] = pack2(sigm_fast(m[0][b2][2 * e]), sigm_fast(m[0][b2][2 * e + 1]));
;       }
;       f32x16 t[1][2]; zero_acc<1>(t);
;       gemm_main<1>(p.G + (size_t)m0 * 1024 + i * 256, 1024, p.WtBr + ((size_t)l * 4 + i) * 1024 * 256 + (size_t)n0 * 256, 256, 256, t, s, tid);
.LBB0_1140:
	s_or_b64 exec, exec, s[0:1]
	v_readlane_b32 s2, v254, 17
	v_readlane_b32 s3, v254, 18
	v_mov_b32_e32 v0, v206
	s_andn2_b64 vcc, exec, s[2:3]
	v_cndmask_b32_e64 v2, 0, 1, s[2:3]
	v_cmp_ne_u32_e64 s[0:1], 1, v2
	v_mov_b32_e32 v149, s48
	s_waitcnt lgkmcnt(0)
	s_barrier
	v_readlane_b32 s18, v254, 19
	v_and_b32_e32 v147, 63, v206
	v_lshrrev_b32_e32 v149, 6, v206
	v_lshrrev_b32_e32 v151, 3, v147
	v_lshl_add_u32 v151, v149, 5, v151
	v_lshlrev_b32_e32 v151, 11, v151
	v_and_b32_e32 v153, 7, v147
	v_lshrrev_b32_e32 v147, 4, v147
	v_xor_b32_e32 v153, v153, v147
	v_lshl_or_b32 v200, v153, 4, v151
	v_xor_b32_e32 v201, 64, v200
	v_add_u32_e32 v201, 16384, v201
	v_add_u32_e32 v202, 32768, v200
	v_add_u32_e32 v203, 32768, v201
	v_and_b32_e32 v147, 63, v206
	v_lshrrev_b32_e32 v149, 6, v206
	v_lshrrev_b32_e32 v151, 3, v147
	v_lshl_add_u32 v151, v149, 5, v151
	v_lshlrev_b32_e32 v151, 9, v151
	v_and_b32_e32 v153, 7, v147
	v_lshrrev_b32_e32 v147, 4, v147
	v_xor_b32_e32 v153, v153, v147
	v_lshl_or_b32 v130, v153, 4, v151
	v_xor_b32_e32 v131, 64, v130
	v_add_u32_e32 v131, 4096, v131
	v_add_u32_e32 v132, 8192, v130
	v_add_u32_e32 v133, 8192, v131
	v_lshrrev_b32_e32 v204, 6, v206
	v_and_b32_e32 v147, 31, v206
	v_bfe_u32 v149, v206, 5, 1
	v_bfe_u32 v151, v147, 1, 3
	v_xor_b32_e32 v151, v151, v149
	v_lshlrev_b32_e32 v151, 4, v151
	v_lshl_or_b32 v151, v147, 7, v151
	v_lshrrev_b32_e32 v153, 7, v206
	v_lshl_add_u32 v138, v153, 13, v151
	v_bfe_u32 v153, v206, 6, 1
	v_lshl_add_u32 v142, v153, 13, v151
	v_add_u32_e32 v142, 0x4000, v142
	v_xor_b32_e32 v139, 32, v138
	v_xor_b32_e32 v143, 32, v142
	v_xor_b32_e32 v140, 64, v138
	v_xor_b32_e32 v144, 64, v142
	v_xor_b32_e32 v141, 96, v138
	v_xor_b32_e32 v145, 96, v142
	v_and_b32_e32 v147, 31, v206
	v_lshrrev_b32_e32 v149, 7, v206
	v_lshl_add_u32 v147, v149, 6, v147
	v_lshlrev_b32_e32 v147, 11, v147
	v_bfe_u32 v149, v206, 6, 1
	v_lshlrev_b32_e32 v149, 7, v149
	v_bfe_u32 v151, v206, 5, 1
	v_lshl_or_b32 v149, v151, 3, v149
	v_or_b32_e32 v146, v147, v149
	v_readfirstlane_b32 s10, v204
	s_lshl_b32 s10, s10, 12
	s_lshl_b32 s6, s18, 23
	s_add_u32 s14, s96, 0x1b720000
	s_addc_u32 s15, s97, 0
	s_add_u32 s14, s14, s6
	s_addc_u32 s15, s15, 0
	s_lshl_b32 s6, s18, 21
	s_add_u32 s16, s96, 0x1c800000
	s_addc_u32 s17, s97, 0
	s_add_u32 s16, s16, s6
	s_addc_u32 s17, s17, 0
	s_mov_b32 s12, s48
.Lmg_item:
	s_cmp_eq_u32 s18, 0
	s_cbranch_scc0 .Lmg_static
	s_barrier
	s_cmp_eq_u32 s10, 0
	s_cbranch_scc0 .Lmg_fetch_wait
	s_mov_b64 s[6:7], exec
	s_mov_b64 exec, 1
	s_add_u32 s8, s96, 0x1da5d500
	s_addc_u32 s9, s97, 0
	v_mov_b32_e32 v147, 1
	v_mov_b32_e32 v149, 0
	global_atomic_add v151, v149, v147, s[8:9] sc0
	v_mov_b32_e32 v153, 0x125f0
	s_waitcnt vmcnt(0)
	ds_write_b32 v153, v151
	s_waitcnt lgkmcnt(0)
	s_mov_b64 exec, s[6:7]
.Lmg_fetch_wait:
	s_barrier
	v_mov_b32_e32 v153, 0x125f0
	ds_read_b32 v151, v153
	s_waitcnt lgkmcnt(0)
	v_readfirstlane_b32 s12, v151
	s_cmpk_lt_u32 s12, 0x880
	s_cbranch_scc0 .Lmg_done
	s_lshr_b32 s19, s12, 3
	s_and_b32 s13, s12, 7
	s_branch .Lmg_decoded
.Lmg_static:
	s_cmpk_lt_u32 s12, 0x800
	s_cbranch_scc0 .Lmg_done
	s_lshr_b32 s6, s12, 8
	s_mul_i32 s6, s6, 34
	s_bfe_u32 s7, s12, 0x50003
	s_add_u32 s19, s6, s7
	s_add_u32 s19, s19, 2
	s_and_b32 s13, s12, 7
.Lmg_decoded:
	s_lshr_b32 s3, s19, 14
	s_lshl_b32 s2, s19, 18
	s_add_u32 s2, s96, s2
	s_addc_u32 s3, s97, s3
	s_lshl_b32 s19, s13, 18
	v_mov_b32_e32 v2, 0
	v_mov_b32_e32 v3, 0
	v_mov_b32_e32 v4, 0
	v_mov_b32_e32 v5, 0
	v_mov_b32_e32 v6, 0
	v_mov_b32_e32 v7, 0
	v_mov_b32_e32 v8, 0
	v_mov_b32_e32 v9, 0
	v_mov_b32_e32 v10, 0
	v_mov_b32_e32 v11, 0
	v_mov_b32_e32 v12, 0
	v_mov_b32_e32 v13, 0
	v_mov_b32_e32 v14, 0
	v_mov_b32_e32 v15, 0
	v_mov_b32_e32 v16, 0
	v_mov_b32_e32 v17, 0
	v_mov_b32_e32 v18, 0
	v_mov_b32_e32 v19, 0
	v_mov_b32_e32 v20, 0
	v_mov_b32_e32 v21, 0
	v_mov_b32_e32 v22, 0
	v_mov_b32_e32 v23, 0
	v_mov_b32_e32 v24, 0
	v_mov_b32_e32 v25, 0
	v_mov_b32_e32 v26, 0
	v_mov_b32_e32 v27, 0
	v_mov_b32_e32 v28, 0
	v_mov_b32_e32 v29, 0
	v_mov_b32_e32 v30, 0
	v_mov_b32_e32 v31, 0
	v_mov_b32_e32 v32, 0
	v_mov_b32_e32 v33, 0
	v_mov_b32_e32 v34, 0
	v_mov_b32_e32 v35, 0
	v_mov_b32_e32 v36, 0
	v_mov_b32_e32 v37, 0
	v_mov_b32_e32 v38, 0
	v_mov_b32_e32 v39, 0
	v_mov_b32_e32 v40, 0
	v_mov_b32_e32 v41, 0
	v_mov_b32_e32 v42, 0
	v_mov_b32_e32 v43, 0
	v_mov_b32_e32 v44, 0
	v_mov_b32_e32 v45, 0
	v_mov_b32_e32 v46, 0
	v_mov_b32_e32 v47, 0
	v_mov_b32_e32 v48, 0
	v_mov_b32_e32 v49, 0
	v_mov_b32_e32 v50, 0
	v_mov_b32_e32 v51, 0
	v_mov_b32_e32 v52, 0
	v_mov_b32_e32 v53, 0
	v_mov_b32_e32 v54, 0
	v_mov_b32_e32 v55, 0
	v_mov_b32_e32 v56, 0
	v_mov_b32_e32 v57, 0
	v_mov_b32_e32 v58, 0
	v_mov_b32_e32 v59, 0
	v_mov_b32_e32 v60, 0
	v_mov_b32_e32 v61, 0
	v_mov_b32_e32 v62, 0
	v_mov_b32_e32 v63, 0
	v_mov_b32_e32 v64, 0
	v_mov_b32_e32 v65, 0
	s_mov_b32 s13, 0
.Lmg_seg:
	s_lshr_b32 s6, s13, 1
	s_bitcmp1_b32 s13, 0
	s_cbranch_scc1 .Lmg_setT
	s_mov_b32 s4, s2
	s_mov_b32 s5, s3
	s_lshl_b32 s7, s6, 21
	s_add_u32 s7, s7, s19
	s_add_u32 s8, s14, s7
	s_addc_u32 s9, s15, 0
	v_mov_b32_e32 v134, v200
	v_mov_b32_e32 v135, v201
	v_mov_b32_e32 v136, v202
	v_mov_b32_e32 v137, v203
	s_mov_b32 s7, 7
	s_branch .Lmg_go
.Lmg_setT:
	s_lshl_b32 s7, s6, 9
	s_add_u32 s4, s2, 0x16720000
	s_addc_u32 s5, s3, 0
	s_add_u32 s4, s4, s7
	s_addc_u32 s5, s5, 0
	s_lshl_b32 s7, s6, 19
	s_lshr_b32 s8, s19, 2
	s_add_u32 s7, s7, s8
	s_add_u32 s8, s16, s7
	s_addc_u32 s9, s17, 0
	v_mov_b32_e32 v134, v130
	v_mov_b32_e32 v135, v131
	v_mov_b32_e32 v136, v132
	v_mov_b32_e32 v137, v133
	s_mov_b32 s7, 1
; #define G_STORE(S, bf) { *(uint4*)&s->a[bf][srow][skc] = S##a0; *(uint4*)&s->a[bf][srow + 32][skc] = S##a1; \
;     if (MB == 2) { *(uint4*)&s->a[bf][srow + 64][skc] = S##a2; *(uint4*)&s->a[bf][srow + 96][skc] = S##a3; } \
;     *(uint4*)&s->b[bf][srow][skc] = S##b0; *(uint4*)&s->b[bf][srow + 32][skc] = S##b1; *(uint4*)&s->b[bf][srow + 64][skc] = S##b2; *(uint4*)&s->b[bf][srow + 96][skc] = S##b3; }
; template <int MB, bool PF2 = true>
; DI void gemm_main(const u16* __restrict__ A, int lda, const u16* __restrict__ B, int ldb, int K, f32x16 (&acc)[MB][2], GemmLds* s, int tid) {
;     ...
;   const int klast = K - 64;
;   G_LOAD(p, 64);
;   __syncthreads();
;   for (int kt = 0; kt < KT; kt += 2) {
;     { const int k2 = min((kt + 2) * 64, klast); G_LOAD(q, k2); }
;     __builtin_amdgcn_sched_barrier(0);
;     G_COMPUTE(0);
;     G_STORE(p, 1);
;     __syncthreads();
;     { const int k3 = min((kt + 3) * 64, klast); G_LOAD(p, k3); }
;     __builtin_amdgcn_sched_barrier(0);
;     G_COMPUTE(1);
;     G_STORE(q, 0);
;     __syncthreads();
;   }
; template <int MB>
; DI void zero_acc(f32x16 (&acc)[MB][2]) {
; #pragma unroll
;   for (int a = 0; a < MB; a++)
; #pragma unroll
;     for (int b = 0; b < 2; b++)
; #pragma unroll
;       for (int i = 0; i < 16; i++) acc[a][b][i] = 0.f;
.Lmg_go:
	v_mov_b32_e32 v66, 0
	v_mov_b32_e32 v67, 0
	v_mov_b32_e32 v68, 0
	v_mov_b32_e32 v69, 0
	v_mov_b32_e32 v70, 0
	v_mov_b32_e32 v71, 0
	v_mov_b32_e32 v72, 0
	v_mov_b32_e32 v73, 0
	v_mov_b32_e32 v74, 0
	v_mov_b32_e32 v75, 0
	v_mov_b32_e32 v76, 0
	v_mov_b32_e32 v77, 0
	v_mov_b32_e32 v78, 0
	v_mov_b32_e32 v79, 0
	v_mov_b32_e32 v80, 0
	v_mov_b32_e32 v81, 0
	v_mov_b32_e32 v82, 0
	v_mov_b32_e32 v83, 0
	v_mov_b32_e32 v84, 0
	v_mov_b32_e32 v85, 0
	v_mov_b32_e32 v86, 0
	v_mov_b32_e32 v87, 0
	v_mov_b32_e32 v88, 0
	v_mov_b32_e32 v89, 0
	v_mov_b32_e32 v90, 0
	v_mov_b32_e32 v91, 0
	v_mov_b32_e32 v92, 0
	v_mov_b32_e32 v93, 0
	v_mov_b32_e32 v94, 0
	v_mov_b32_e32 v95, 0
	v_mov_b32_e32 v96, 0
	v_mov_b32_e32 v97, 0
	v_mov_b32_e32 v98, 0
	v_mov_b32_e32 v99, 0
	v_mov_b32_e32 v100, 0
	v_mov_b32_e32 v101, 0
	v_mov_b32_e32 v102, 0
	v_mov_b32_e32 v103, 0
	v_mov_b32_e32 v104, 0
	v_mov_b32_e32 v105, 0
	v_mov_b32_e32 v106, 0
	v_mov_b32_e32 v107, 0
	v_mov_b32_e32 v108, 0
	v_mov_b32_e32 v109, 0
	v_mov_b32_e32 v110, 0
	v_mov_b32_e32 v111, 0
	v_mov_b32_e32 v112, 0
	v_mov_b32_e32 v113, 0
	v_mov_b32_e32 v114, 0
	v_mov_b32_e32 v115, 0
	v_mov_b32_e32 v116, 0
	v_mov_b32_e32 v117, 0
	v_mov_b32_e32 v118, 0
	v_mov_b32_e32 v119, 0
	v_mov_b32_e32 v120, 0
	v_mov_b32_e32 v121, 0
	v_mov_b32_e32 v122, 0
	v_mov_b32_e32 v123, 0
	v_mov_b32_e32 v124, 0
	v_mov_b32_e32 v125, 0
	v_mov_b32_e32 v126, 0
	v_mov_b32_e32 v127, 0
	v_mov_b32_e32 v128, 0
	v_mov_b32_e32 v129, 0
	s_add_u32 m0, s10, 0x0
	s_nop 0
	global_load_lds_dwordx4 v200, s[4:5]
	s_add_u32 m0, s10, 0x400
	s_nop 0
	global_load_lds_dwordx4 v201, s[4:5]
	s_add_u32 m0, s10, 0x800
	s_nop 0
	global_load_lds_dwordx4 v202, s[4:5]
	s_add_u32 m0, s10, 0xc00
	s_nop 0
	global_load_lds_dwordx4 v203, s[4:5]
	s_add_u32 m0, s10, 0x4000
	s_nop 0
	global_load_lds_dwordx4 v134, s[8:9]
	s_add_u32 m0, s10, 0x4400
	s_nop 0
	global_load_lds_dwordx4 v135, s[8:9]
	s_add_u32 m0, s10, 0x4800
	s_nop 0
	global_load_lds_dwordx4 v136, s[8:9]
	s_add_u32 m0, s10, 0x4c00
	s_nop 0
	global_load_lds_dwordx4 v137, s[8:9]
	s_add_u32 s4, s4, 128
	s_addc_u32 s5, s5, 0
	s_add_u32 s8, s8, 128
	s_addc_u32 s9, s9, 0
	s_waitcnt vmcnt(0) lgkmcnt(0)
	s_barrier
	ds_read_b128 v[224:227], v138 offset:0
	ds_read_b128 v[232:235], v142 offset:0
	ds_read_b128 v[228:231], v138 offset:4096
	ds_read_b128 v[236:239], v142 offset:4096
	s_mov_b32 s11, s7
.Lmg_loop:
	s_add_u32 m0, s10, 0x8000
	ds_read_b128 v[240:243], v139 offset:0
	global_load_lds_dwordx4 v200, s[4:5]
	s_add_u32 m0, s10, 0x8400
	ds_read_b128 v[192:195], v143 offset:0
	global_load_lds_dwordx4 v201, s[4:5]
	s_add_u32 m0, s10, 0x8800
	ds_read_b128 v[188:191], v139 offset:4096
	global_load_lds_dwordx4 v202, s[4:5]
	s_add_u32 m0, s10, 0x8c00
	ds_read_b128 v[196:199], v143 offset:4096
	global_load_lds_dwordx4 v203, s[4:5]
	s_add_u32 m0, s10, 0xc000
	s_add_u32 s4, s4, 128
	s_addc_u32 s5, s5, 0
	global_load_lds_dwordx4 v134, s[8:9]
	s_add_u32 m0, s10, 0xc400
	s_nop 0
	global_load_lds_dwordx4 v135, s[8:9]
	s_add_u32 m0, s10, 0xc800
	s_nop 0
	global_load_lds_dwordx4 v136, s[8:9]
	s_add_u32 m0, s10, 0xcc00
	s_nop 0
	global_load_lds_dwordx4 v137, s[8:9]
	s_add_u32 s8, s8, 128
	s_addc_u32 s9, s9, 0
	s_waitcnt lgkmcnt(4)
	v_mfma_f32_32x32x16_bf16 v[66:81], v[232:235], v[224:227], v[66:81]
	v_mfma_f32_32x32x16_bf16 v[82:97], v[236:239], v[224:227], v[82:97]
	v_mfma_f32_32x32x16_bf16 v[98:113], v[232:235], v[228:231], v[98:113]
	v_mfma_f32_32x32x16_bf16 v[114:129], v[236:239], v[228:231], v[114:129]
	ds_read_b128 v[224:227], v140 offset:0
	ds_read_b128 v[232:235], v144 offset:0
	ds_read_b128 v[228:231], v140 offset:4096
	ds_read_b128 v[236:239], v144 offset:4096
	s_waitcnt lgkmcnt(4)
	v_mfma_f32_32x32x16_bf16 v[66:81], v[192:195], v[240:243], v[66:81]
	v_mfma_f32_32x32x16_bf16 v[82:97], v[196:199], v[240:243], v[82:97]
	v_mfma_f32_32x32x16_bf16 v[98:113], v[192:195], v[188:191], v[98:113]
	v_mfma_f32_32x32x16_bf16 v[114:129], v[196:199], v[188:191], v[114:129]
	ds_read_b128 v[240:243], v141 offset:0
	ds_read_b128 v[192:195], v145 offset:0
	ds_read_b128 v[188:191], v141 offset:4096
	ds_read_b128 v[196:199], v145 offset:4096
	s_waitcnt lgkmcnt(4)
	v_mfma_f32_32x32x16_bf16 v[66:81], v[232:235], v[224:227], v[66:81]
	v_mfma_f32_32x32x16_bf16 v[82:97], v[236:239], v[224:227], v[82:97]
	v_mfma_f32_32x32x16_bf16 v[98:113], v[232:235], v[228:231], v[98:113]
	v_mfma_f32_32x32x16_bf16 v[114:129], v[236:239], v[228:231], v[114:129]
	s_waitcnt vmcnt(0) lgkmcnt(0)
	s_barrier
	ds_read_b128 v[224:227], v138 offset:32768
	ds_read_b128 v[232:235], v142 offset:32768
	ds_read_b128 v[228:231], v138 offset:36864
	ds_read_b128 v[236:239], v142 offset:36864
	v_mfma_f32_32x32x16_bf16 v[66:81], v[192:195], v[240:243], v[66:81]
	v_mfma_f32_32x32x16_bf16 v[82:97], v[196:199], v[240:243], v[82:97]
	v_mfma_f32_32x32x16_bf16 v[98:113], v[192:195], v[188:191], v[98:113]
	v_mfma_f32_32x32x16_bf16 v[114:129], v[196:199], v[188:191], v[114:129]
	s_cmp_eq_u32 s11, 0
	s_cbranch_scc1 .Lmg_last
; #define G_STORE(S, bf) { *(uint4*)&s->a[bf][srow][skc] = S##a0; *(uint4*)&s->a[bf][srow + 32][skc] = S##a1; \
;     if (MB == 2) { *(uint4*)&s->a[bf][srow + 64][skc] = S##a2; *(uint4*)&s->a[bf][srow + 96][skc] = S##a3; } \
;     *(uint4*)&s->b[bf][srow][skc] = S##b0; *(uint4*)&s->b[bf][srow + 32][skc] = S##b1; *(uint4*)&s->b[bf][srow + 64][skc] = S##b2; *(uint4*)&s->b[bf][srow + 96][skc] = S##b3; }
; template <int MB, bool PF2 = true>
; DI void gemm_main(const u16* __restrict__ A, int lda, const u16* __restrict__ B, int ldb, int K, f32x16 (&acc)[MB][2], GemmLds* s, int tid) {
;     ...
;   for (int kt = 0; kt < KT; kt += 2) {
;     { const int k2 = min((kt + 2) * 64, klast); G_LOAD(q, k2); }
;     __builtin_amdgcn_sched_barrier(0);
;     G_COMPUTE(0);
;     G_STORE(p, 1);
;     __syncthreads();
;     { const int k3 = min((kt + 3) * 64, klast); G_LOAD(p, k3); }
;     __builtin_amdgcn_sched_barrier(0);
;     G_COMPUTE(1);
;     G_STORE(q, 0);
;     __syncthreads();
;   }
	s_add_u32 m0, s10, 0x0
	ds_read_b128 v[240:243], v139 offset:32768
	global_load_lds_dwordx4 v200, s[4:5]
	s_add_u32 m0, s10, 0x400
	ds_read_b128 v[192:195], v143 offset:32768
	global_load_lds_dwordx4 v201, s[4:5]
	s_add_u32 m0, s10, 0x800
	ds_read_b128 v[188:191], v139 offset:36864
	global_load_lds_dwordx4 v202, s[4:5]
	s_add_u32 m0, s10, 0xc00
	ds_read_b128 v[196:199], v143 offset:36864
	global_load_lds_dwordx4 v203, s[4:5]
	s_add_u32 m0, s10, 0x4000
	s_add_u32 s4, s4, 128
	s_addc_u32 s5, s5, 0
	global_load_lds_dwordx4 v134, s[8:9]
	s_add_u32 m0, s10, 0x4400
	s_nop 0
	global_load_lds_dwordx4 v135, s[8:9]
	s_add_u32 m0, s10, 0x4800
	s_nop 0
	global_load_lds_dwordx4 v136, s[8:9]
	s_add_u32 m0, s10, 0x4c00
	s_nop 0
	global_load_lds_dwordx4 v137, s[8:9]
	s_add_u32 s8, s8, 128
	s_addc_u32 s9, s9, 0
	s_waitcnt lgkmcnt(4)
	v_mfma_f32_32x32x16_bf16 v[66:81], v[232:235], v[224:227], v[66:81]
	v_mfma_f32_32x32x16_bf16 v[82:97], v[236:239], v[224:227], v[82:97]
	v_mfma_f32_32x32x16_bf16 v[98:113], v[232:235], v[228:231], v[98:113]
	v_mfma_f32_32x32x16_bf16 v[114:129], v[236:239], v[228:231], v[114:129]
	ds_read_b128 v[224:227], v140 offset:32768
	ds_read_b128 v[232:235], v144 offset:32768
	ds_read_b128 v[228:231], v140 offset:36864
	ds_read_b128 v[236:239], v144 offset:36864
	s_waitcnt lgkmcnt(4)
	v_mfma_f32_32x32x16_bf16 v[66:81], v[192:195], v[240:243], v[66:81]
	v_mfma_f32_32x32x16_bf16 v[82:97], v[196:199], v[240:243], v[82:97]
	v_mfma_f32_32x32x16_bf16 v[98:113], v[192:195], v[188:191], v[98:113]
	v_mfma_f32_32x32x16_bf16 v[114:129], v[196:199], v[188:191], v[114:129]
	ds_read_b128 v[240:243], v141 offset:32768
	ds_read_b128 v[192:195], v145 offset:32768
	ds_read_b128 v[188:191], v141 offset:36864
	ds_read_b128 v[196:199], v145 offset:36864
	s_waitcnt lgkmcnt(4)
	v_mfma_f32_32x32x16_bf16 v[66:81], v[232:235], v[224:227], v[66:81]
	v_mfma_f32_32x32x16_bf16 v[82:97], v[236:239], v[224:227], v[82:97]
	v_mfma_f32_32x32x16_bf16 v[98:113], v[232:235], v[228:231], v[98:113]
	v_mfma_f32_32x32x16_bf16 v[114:129], v[236:239], v[228:231], v[114:129]
	s_waitcnt vmcnt(0) lgkmcnt(0)
	s_barrier
	ds_read_b128 v[224:227], v138 offset:0
	ds_read_b128 v[232:235], v142 offset:0
	ds_read_b128 v[228:231], v138 offset:4096
	ds_read_b128 v[236:239], v142 offset:4096
	v_mfma_f32_32x32x16_bf16 v[66:81], v[192:195], v[240:243], v[66:81]
	v_mfma_f32_32x32x16_bf16 v[82:97], v[196:199], v[240:243], v[82:97]
	v_mfma_f32_32x32x16_bf16 v[98:113], v[192:195], v[188:191], v[98:113]
	v_mfma_f32_32x32x16_bf16 v[114:129], v[196:199], v[188:191], v[114:129]
	s_sub_u32 s11, s11, 1
	s_branch .Lmg_loop
.Lmg_last:
	ds_read_b128 v[240:243], v139 offset:32768
	ds_read_b128 v[192:195], v143 offset:32768
	ds_read_b128 v[188:191], v139 offset:36864
	ds_read_b128 v[196:199], v143 offset:36864
	s_waitcnt lgkmcnt(4)
	v_mfma_f32_32x32x16_bf16 v[66:81], v[232:235], v[224:227], v[66:81]
	v_mfma_f32_32x32x16_bf16 v[82:97], v[236:239], v[224:227], v[82:97]
	v_mfma_f32_32x32x16_bf16 v[98:113], v[232:235], v[228:231], v[98:113]
	v_mfma_f32_32x32x16_bf16 v[114:129], v[236:239], v[228:231], v[114:129]
	ds_read_b128 v[224:227], v140 offset:32768
	ds_read_b128 v[232:235], v144 offset:32768
	ds_read_b128 v[228:231], v140 offset:36864
	ds_read_b128 v[236:239], v144 offset:36864
	s_waitcnt lgkmcnt(4)
	v_mfma_f32_32x32x16_bf16 v[66:81], v[192:195], v[240:243], v[66:81]
	v_mfma_f32_32x32x16_bf16 v[82:97], v[196:199], v[240:243], v[82:97]
	v_mfma_f32_32x32x16_bf16 v[98:113], v[192:195], v[188:191], v[98:113]
	v_mfma_f32_32x32x16_bf16 v[114:129], v[196:199], v[188:191], v[114:129]
	ds_read_b128 v[240:243], v141 offset:32768
	ds_read_b128 v[192:195], v145 offset:32768
	ds_read_b128 v[188:191], v141 offset:36864
	ds_read_b128 v[196:199], v145 offset:36864
	s_waitcnt lgkmcnt(4)
	v_mfma_f32_32x32x16_bf16 v[66:81], v[232:235], v[224:227], v[66:81]
	v_mfma_f32_32x32x16_bf16 v[82:97], v[236:239], v[224:227], v[82:97]
	v_mfma_f32_32x32x16_bf16 v[98:113], v[232:235], v[228:231], v[98:113]
	v_mfma_f32_32x32x16_bf16 v[114:129], v[236:239], v[228:231], v[114:129]
	s_waitcnt vmcnt(0) lgkmcnt(0)
	s_barrier
	v_mfma_f32_32x32x16_bf16 v[66:81], v[192:195], v[240:243], v[66:81]
	v_mfma_f32_32x32x16_bf16 v[82:97], v[196:199], v[240:243], v[82:97]
	v_mfma_f32_32x32x16_bf16 v[98:113], v[192:195], v[188:191], v[98:113]
	v_mfma_f32_32x32x16_bf16 v[114:129], v[196:199], v[188:191], v[114:129]
	s_nop 7
	s_nop 7
	s_bitcmp1_b32 s13, 0
	s_cbranch_scc1 .Lmg_postT
; DI unsigned pack2(float a, float b) { f32v2 v = {a, b}; return __builtin_bit_cast(unsigned, __builtin_convertvector(v, bf16v2)); }
; DI float sigm(float x) { return __builtin_amdgcn_rcpf(1.f + __expf(-x)); }
; DI float silu(float x) { return x * sigm(x); }
; DI float sigm_fast(float x) { return __builtin_amdgcn_rcpf(1.f + __expf(-x)); }
; DI void phase_merge(const Params& p, int l, char* smem, int tid) {
;     ...
; #pragma unroll
;         for (int b2 = 0; b2 < 2; b2++)
; #pragma unroll
;           for (int e = 0; e < 8; e++) sg[b2][e] = pack2(sigm_fast(m[0][b2][2 * e]), sigm_fast(m[0][b2][2 * e + 1]));
	v_mul_f32_e32 v66, 0xbfb8aa3b, v66
	v_mul_f32_e32 v67, 0xbfb8aa3b, v67
	v_mul_f32_e32 v68, 0xbfb8aa3b, v68
	v_mul_f32_e32 v69, 0xbfb8aa3b, v69
	v_mul_f32_e32 v70, 0xbfb8aa3b, v70
	v_mul_f32_e32 v71, 0xbfb8aa3b, v71
	v_mul_f32_e32 v72, 0xbfb8aa3b, v72
	v_mul_f32_e32 v73, 0xbfb8aa3b, v73
	v_exp_f32_e32 v66, v66
	v_exp_f32_e32 v67, v67
	v_exp_f32_e32 v68, v68
	v_exp_f32_e32 v69, v69
	v_exp_f32_e32 v70, v70
	v_exp_f32_e32 v71, v71
	v_exp_f32_e32 v72, v72
	v_exp_f32_e32 v73, v73
	v_add_f32_e32 v66, 1.0, v66
	v_add_f32_e32 v67, 1.0, v67
	v_add_f32_e32 v68, 1.0, v68
	v_add_f32_e32 v69, 1.0, v69
	v_add_f32_e32 v70, 1.0, v70
	v_add_f32_e32 v71, 1.0, v71
	v_add_f32_e32 v72, 1.0, v72
	v_add_f32_e32 v73, 1.0, v73
	v_rcp_f32_e32 v66, v66
	v_rcp_f32_e32 v67, v67
	v_rcp_f32_e32 v68, v68
	v_rcp_f32_e32 v69, v69
	v_rcp_f32_e32 v70, v70
	v_rcp_f32_e32 v71, v71
	v_rcp_f32_e32 v72, v72
	v_rcp_f32_e32 v73, v73
	s_nop 0
	v_cvt_pk_bf16_f32 v156, v66, v67
	v_cvt_pk_bf16_f32 v157, v68, v69
	v_cvt_pk_bf16_f32 v158, v70, v71
	v_cvt_pk_bf16_f32 v159, v72, v73
	v_mul_f32_e32 v74, 0xbfb8aa3b, v74
	v_mul_f32_e32 v75, 0xbfb8aa3b, v75
	v_mul_f32_e32 v76, 0xbfb8aa3b, v76
	v_mul_f32_e32 v77, 0xbfb8aa3b, v77
	v_mul_f32_e32 v78, 0xbfb8aa3b, v78
	v_mul_f32_e32 v79, 0xbfb8aa3b, v79
	v_mul_f32_e32 v80, 0xbfb8aa3b, v80
	v_mul_f32_e32 v81, 0xbfb8aa3b, v81
	v_exp_f32_e32 v74, v74
	v_exp_f32_e32 v75, v75
	v_exp_f32_e32 v76, v76
	v_exp_f32_e32 v77, v77
	v_exp_f32_e32 v78, v78
	v_exp_f32_e32 v79, v79
	v_exp_f32_e32 v80, v80
	v_exp_f32_e32 v81, v81
	v_add_f32_e32 v74, 1.0, v74
	v_add_f32_e32 v75, 1.0, v75
	v_add_f32_e32 v76, 1.0, v76
	v_add_f32_e32 v77, 1.0, v77
	v_add_f32_e32 v78, 1.0, v78
	v_add_f32_e32 v79, 1.0, v79
	v_add_f32_e32 v80, 1.0, v80
	v_add_f32_e32 v81, 1.0, v81
	v_rcp_f32_e32 v74, v74
	v_rcp_f32_e32 v75, v75
	v_rcp_f32_e32 v76, v76
	v_rcp_f32_e32 v77, v77
	v_rcp_f32_e32 v78, v78
	v_rcp_f32_e32 v79, v79
	v_rcp_f32_e32 v80, v80
	v_rcp_f32_e32 v81, v81
	s_nop 0
	v_cvt_pk_bf16_f32 v160, v74, v75
	v_cvt_pk_bf16_f32 v161, v76, v77
	v_cvt_pk_bf16_f32 v162, v78, v79
	v_cvt_pk_bf16_f32 v163, v80, v81
	v_mul_f32_e32 v82, 0xbfb8aa3b, v82
	v_mul_f32_e32 v83, 0xbfb8aa3b, v83
	v_mul_f32_e32 v84, 0xbfb8aa3b, v84
	v_mul_f32_e32 v85, 0xbfb8aa3b, v85
	v_mul_f32_e32 v86, 0xbfb8aa3b, v86
	v_mul_f32_e32 v87, 0xbfb8aa3b, v87
	v_mul_f32_e32 v88, 0xbfb8aa3b, v88
	v_mul_f32_e32 v89, 0xbfb8aa3b, v89
	v_exp_f32_e32 v82, v82
	v_exp_f32_e32 v83, v83
	v_exp_f32_e32 v84, v84
	v_exp_f32_e32 v85, v85
	v_exp_f32_e32 v86, v86
	v_exp_f32_e32 v87, v87
	v_exp_f32_e32 v88, v88
	v_exp_f32_e32 v89, v89
	v_add_f32_e32 v82, 1.0, v82
	v_add_f32_e32 v83, 1.0, v83
	v_add_f32_e32 v84, 1.0, v84
	v_add_f32_e32 v85, 1.0, v85
	v_add_f32_e32 v86, 1.0, v86
	v_add_f32_e32 v87, 1.0, v87
	v_add_f32_e32 v88, 1.0, v88
	v_add_f32_e32 v89, 1.0, v89
	v_rcp_f32_e32 v82, v82
	v_rcp_f32_e32 v83, v83
	v_rcp_f32_e32 v84, v84
	v_rcp_f32_e32 v85, v85
	v_rcp_f32_e32 v86, v86
	v_rcp_f32_e32 v87, v87
	v_rcp_f32_e32 v88, v88
	v_rcp_f32_e32 v89, v89
	s_nop 0
	v_cvt_pk_bf16_f32 v164, v82, v83
	v_cvt_pk_bf16_f32 v165, v84, v85
	v_cvt_pk_bf16_f32 v166, v86, v87
	v_cvt_pk_bf16_f32 v167, v88, v89
	v_mul_f32_e32 v90, 0xbfb8aa3b, v90
	v_mul_f32_e32 v91, 0xbfb8aa3b, v91
	v_mul_f32_e32 v92, 0xbfb8aa3b, v92
	v_mul_f32_e32 v93, 0xbfb8aa3b, v93
	v_mul_f32_e32 v94, 0xbfb8aa3b, v94
	v_mul_f32_e32 v95, 0xbfb8aa3b, v95
	v_mul_f32_e32 v96, 0xbfb8aa3b, v96
	v_mul_f32_e32 v97, 0xbfb8aa3b, v97
	v_exp_f32_e32 v90, v90
	v_exp_f32_e32 v91, v91
	v_exp_f32_e32 v92, v92
	v_exp_f32_e32 v93, v93
	v_exp_f32_e32 v94, v94
	v_exp_f32_e32 v95, v95
	v_exp_f32_e32 v96, v96
	v_exp_f32_e32 v97, v97
	v_add_f32_e32 v90, 1.0, v90
	v_add_f32_e32 v91, 1.0, v91
	v_add_f32_e32 v92, 1.0, v92
	v_add_f32_e32 v93, 1.0, v93
	v_add_f32_e32 v94, 1.0, v94
	v_add_f32_e32 v95, 1.0, v95
	v_add_f32_e32 v96, 1.0, v96
	v_add_f32_e32 v97, 1.0, v97
	v_rcp_f32_e32 v90, v90
	v_rcp_f32_e32 v91, v91
	v_rcp_f32_e32 v92, v92
	v_rcp_f32_e32 v93, v93
	v_rcp_f32_e32 v94, v94
	v_rcp_f32_e32 v95, v95
	v_rcp_f32_e32 v96, v96
	v_rcp_f32_e32 v97, v97
	s_nop 0
	v_cvt_pk_bf16_f32 v168, v90, v91
	v_cvt_pk_bf16_f32 v169, v92, v93
	v_cvt_pk_bf16_f32 v170, v94, v95
	v_cvt_pk_bf16_f32 v171, v96, v97
	v_mul_f32_e32 v98, 0xbfb8aa3b, v98
	v_mul_f32_e32 v99, 0xbfb8aa3b, v99
	v_mul_f32_e32 v100, 0xbfb8aa3b, v100
	v_mul_f32_e32 v101, 0xbfb8aa3b, v101
	v_mul_f32_e32 v102, 0xbfb8aa3b, v102
	v_mul_f32_e32 v103, 0xbfb8aa3b, v103
	v_mul_f32_e32 v104, 0xbfb8aa3b, v104
	v_mul_f32_e32 v105, 0xbfb8aa3b, v105
	v_exp_f32_e32 v98, v98
	v_exp_f32_e32 v99, v99
	v_exp_f32_e32 v100, v100
	v_exp_f32_e32 v101, v101
	v_exp_f32_e32 v102, v102
	v_exp_f32_e32 v103, v103
	v_exp_f32_e32 v104, v104
	v_exp_f32_e32 v105, v105
	v_add_f32_e32 v98, 1.0, v98
	v_add_f32_e32 v99, 1.0, v99
	v_add_f32_e32 v100, 1.0, v100
	v_add_f32_e32 v101, 1.0, v101
	v_add_f32_e32 v102, 1.0, v102
	v_add_f32_e32 v103, 1.0, v103
	v_add_f32_e32 v104, 1.0, v104
	v_add_f32_e32 v105, 1.0, v105
	v_rcp_f32_e32 v98, v98
	v_rcp_f32_e32 v99, v99
	v_rcp_f32_e32 v100, v100
	v_rcp_f32_e32 v101, v101
	v_rcp_f32_e32 v102, v102
	v_rcp_f32_e32 v103, v103
	v_rcp_f32_e32 v104, v104
	v_rcp_f32_e32 v105, v105
	s_nop 0
	v_cvt_pk_bf16_f32 v172, v98, v99
	v_cvt_pk_bf16_f32 v173, v100, v101
	v_cvt_pk_bf16_f32 v174, v102, v103
	v_cvt_pk_bf16_f32 v175, v104, v105
	v_mul_f32_e32 v106, 0xbfb8aa3b, v106
	v_mul_f32_e32 v107, 0xbfb8aa3b, v107
	v_mul_f32_e32 v108, 0xbfb8aa3b, v108
	v_mul_f32_e32 v109, 0xbfb8aa3b, v109
	v_mul_f32_e32 v110, 0xbfb8aa3b, v110
	v_mul_f32_e32 v111, 0xbfb8aa3b, v111
	v_mul_f32_e32 v112, 0xbfb8aa3b, v112
	v_mul_f32_e32 v113, 0xbfb8aa3b, v113
	v_exp_f32_e32 v106, v106
; DI unsigned pack2(float a, float b) { f32v2 v = {a, b}; return __builtin_bit_cast(unsigned, __builtin_convertvector(v, bf16v2)); }
; DI float sigm_fast(float x) { return __builtin_amdgcn_rcpf(1.f + __expf(-x)); }
; DI void phase_merge(const Params& p, int l, char* smem, int tid) {
;     ...
; #pragma unroll
;         for (int b2 = 0; b2 < 2; b2++)
; #pragma unroll
;           for (int e = 0; e < 8; e++) sg[b2][e] = pack2(sigm_fast(m[0][b2][2 * e]), sigm_fast(m[0][b2][2 * e + 1]));
	v_exp_f32_e32 v107, v107
	v_exp_f32_e32 v108, v108
	v_exp_f32_e32 v109, v109
	v_exp_f32_e32 v110, v110
	v_exp_f32_e32 v111, v111
	v_exp_f32_e32 v112, v112
	v_exp_f32_e32 v113, v113
	v_add_f32_e32 v106, 1.0, v106
	v_add_f32_e32 v107, 1.0, v107
	v_add_f32_e32 v108, 1.0, v108
	v_add_f32_e32 v109, 1.0, v109
	v_add_f32_e32 v110, 1.0, v110
	v_add_f32_e32 v111, 1.0, v111
	v_add_f32_e32 v112, 1.0, v112
	v_add_f32_e32 v113, 1.0, v113
	v_rcp_f32_e32 v106, v106
	v_rcp_f32_e32 v107, v107
	v_rcp_f32_e32 v108, v108
	v_rcp_f32_e32 v109, v109
	v_rcp_f32_e32 v110, v110
	v_rcp_f32_e32 v111, v111
	v_rcp_f32_e32 v112, v112
	v_rcp_f32_e32 v113, v113
	s_nop 0
	v_cvt_pk_bf16_f32 v176, v106, v107
	v_cvt_pk_bf16_f32 v177, v108, v109
	v_cvt_pk_bf16_f32 v178, v110, v111
	v_cvt_pk_bf16_f32 v179, v112, v113
	v_mul_f32_e32 v114, 0xbfb8aa3b, v114
	v_mul_f32_e32 v115, 0xbfb8aa3b, v115
	v_mul_f32_e32 v116, 0xbfb8aa3b, v116
	v_mul_f32_e32 v117, 0xbfb8aa3b, v117
	v_mul_f32_e32 v118, 0xbfb8aa3b, v118
	v_mul_f32_e32 v119, 0xbfb8aa3b, v119
	v_mul_f32_e32 v120, 0xbfb8aa3b, v120
	v_mul_f32_e32 v121, 0xbfb8aa3b, v121
	v_exp_f32_e32 v114, v114
	v_exp_f32_e32 v115, v115
	v_exp_f32_e32 v116, v116
	v_exp_f32_e32 v117, v117
	v_exp_f32_e32 v118, v118
	v_exp_f32_e32 v119, v119
	v_exp_f32_e32 v120, v120
	v_exp_f32_e32 v121, v121
	v_add_f32_e32 v114, 1.0, v114
	v_add_f32_e32 v115, 1.0, v115
	v_add_f32_e32 v116, 1.0, v116
	v_add_f32_e32 v117, 1.0, v117
	v_add_f32_e32 v118, 1.0, v118
	v_add_f32_e32 v119, 1.0, v119
	v_add_f32_e32 v120, 1.0, v120
	v_add_f32_e32 v121, 1.0, v121
	v_rcp_f32_e32 v114, v114
	v_rcp_f32_e32 v115, v115
	v_rcp_f32_e32 v116, v116
	v_rcp_f32_e32 v117, v117
	v_rcp_f32_e32 v118, v118
	v_rcp_f32_e32 v119, v119
	v_rcp_f32_e32 v120, v120
	v_rcp_f32_e32 v121, v121
	s_nop 0
	v_cvt_pk_bf16_f32 v180, v114, v115
	v_cvt_pk_bf16_f32 v181, v116, v117
	v_cvt_pk_bf16_f32 v182, v118, v119
	v_cvt_pk_bf16_f32 v183, v120, v121
	v_mul_f32_e32 v122, 0xbfb8aa3b, v122
	v_mul_f32_e32 v123, 0xbfb8aa3b, v123
	v_mul_f32_e32 v124, 0xbfb8aa3b, v124
	v_mul_f32_e32 v125, 0xbfb8aa3b, v125
	v_mul_f32_e32 v126, 0xbfb8aa3b, v126
	v_mul_f32_e32 v127, 0xbfb8aa3b, v127
	v_mul_f32_e32 v128, 0xbfb8aa3b, v128
	v_mul_f32_e32 v129, 0xbfb8aa3b, v129
	v_exp_f32_e32 v122, v122
	v_exp_f32_e32 v123, v123
	v_exp_f32_e32 v124, v124
	v_exp_f32_e32 v125, v125
	v_exp_f32_e32 v126, v126
	v_exp_f32_e32 v127, v127
	v_exp_f32_e32 v128, v128
	v_exp_f32_e32 v129, v129
	v_add_f32_e32 v122, 1.0, v122
	v_add_f32_e32 v123, 1.0, v123
	v_add_f32_e32 v124, 1.0, v124
	v_add_f32_e32 v125, 1.0, v125
	v_add_f32_e32 v126, 1.0, v126
	v_add_f32_e32 v127, 1.0, v127
	v_add_f32_e32 v128, 1.0, v128
	v_add_f32_e32 v129, 1.0, v129
	v_rcp_f32_e32 v122, v122
	v_rcp_f32_e32 v123, v123
	v_rcp_f32_e32 v124, v124
	v_rcp_f32_e32 v125, v125
	v_rcp_f32_e32 v126, v126
	v_rcp_f32_e32 v127, v127
	v_rcp_f32_e32 v128, v128
	v_rcp_f32_e32 v129, v129
	s_nop 0
	v_cvt_pk_bf16_f32 v184, v122, v123
	v_cvt_pk_bf16_f32 v185, v124, v125
	v_cvt_pk_bf16_f32 v186, v126, v127
	v_cvt_pk_bf16_f32 v187, v128, v129
	s_branch .Lmg_segnext
; DI u16 f2bf(float x) { return (u16)(pack2(x, 0.f) & 0xffffu); }
; DI float bflo(unsigned v) { return __uint_as_float(v << 16); }
; DI float bfhi(unsigned v) { return __uint_as_float(v & 0xffff0000u); }
; DI int crow(int i, int h) { return (i & 3) + 8 * (i >> 2) + 4 * h; }
; DI void phase_merge(const Params& p, int l, char* smem, int tid) {
;     ...
; #pragma unroll
;       for (int b2 = 0; b2 < 2; b2++)
; #pragma unroll
;         for (int e = 0; e < 8; e++) { accT[0][b2][2 * e] += bflo(sg[b2][e]) * t[0][b2][2 * e]; accT[0][b2][2 * e + 1] += bfhi(sg[b2][e]) * t[0][b2][2 * e + 1]; }
;     }
; #pragma unroll
;     for (int nb = 0; nb < 2; nb++) {
;       const int rowb = m0 + wm * 32, col = n0 + wn * 64 + nb * 32 + r;
; #pragma unroll
;       for (int i = 0; i < 16; i++) ACC[(size_t)(rowb + crow(i, h)) * 1024 + col] = f2bf(accT[0][nb][i]);
;     }
.Lmg_postT:
	v_lshlrev_b32_e32 v147, 16, v156
	v_and_b32_e32 v149, 0xffff0000, v156
	v_fmac_f32_e32 v2, v147, v66
	v_fmac_f32_e32 v3, v149, v67
	v_lshlrev_b32_e32 v151, 16, v157
	v_and_b32_e32 v153, 0xffff0000, v157
	v_fmac_f32_e32 v4, v151, v68
	v_fmac_f32_e32 v5, v153, v69
	v_lshlrev_b32_e32 v147, 16, v158
	v_and_b32_e32 v149, 0xffff0000, v158
	v_fmac_f32_e32 v6, v147, v70
	v_fmac_f32_e32 v7, v149, v71
	v_lshlrev_b32_e32 v151, 16, v159
	v_and_b32_e32 v153, 0xffff0000, v159
	v_fmac_f32_e32 v8, v151, v72
	v_fmac_f32_e32 v9, v153, v73
	v_lshlrev_b32_e32 v147, 16, v160
	v_and_b32_e32 v149, 0xffff0000, v160
	v_fmac_f32_e32 v10, v147, v74
	v_fmac_f32_e32 v11, v149, v75
	v_lshlrev_b32_e32 v151, 16, v161
	v_and_b32_e32 v153, 0xffff0000, v161
	v_fmac_f32_e32 v12, v151, v76
	v_fmac_f32_e32 v13, v153, v77
	v_lshlrev_b32_e32 v147, 16, v162
	v_and_b32_e32 v149, 0xffff0000, v162
	v_fmac_f32_e32 v14, v147, v78
	v_fmac_f32_e32 v15, v149, v79
	v_lshlrev_b32_e32 v151, 16, v163
	v_and_b32_e32 v153, 0xffff0000, v163
	v_fmac_f32_e32 v16, v151, v80
	v_fmac_f32_e32 v17, v153, v81
	v_lshlrev_b32_e32 v147, 16, v164
	v_and_b32_e32 v149, 0xffff0000, v164
	v_fmac_f32_e32 v18, v147, v82
	v_fmac_f32_e32 v19, v149, v83
	v_lshlrev_b32_e32 v151, 16, v165
	v_and_b32_e32 v153, 0xffff0000, v165
	v_fmac_f32_e32 v20, v151, v84
	v_fmac_f32_e32 v21, v153, v85
	v_lshlrev_b32_e32 v147, 16, v166
	v_and_b32_e32 v149, 0xffff0000, v166
	v_fmac_f32_e32 v22, v147, v86
	v_fmac_f32_e32 v23, v149, v87
	v_lshlrev_b32_e32 v151, 16, v167
	v_and_b32_e32 v153, 0xffff0000, v167
	v_fmac_f32_e32 v24, v151, v88
	v_fmac_f32_e32 v25, v153, v89
	v_lshlrev_b32_e32 v147, 16, v168
	v_and_b32_e32 v149, 0xffff0000, v168
	v_fmac_f32_e32 v26, v147, v90
	v_fmac_f32_e32 v27, v149, v91
	v_lshlrev_b32_e32 v151, 16, v169
	v_and_b32_e32 v153, 0xffff0000, v169
	v_fmac_f32_e32 v28, v151, v92
	v_fmac_f32_e32 v29, v153, v93
	v_lshlrev_b32_e32 v147, 16, v170
	v_and_b32_e32 v149, 0xffff0000, v170
	v_fmac_f32_e32 v30, v147, v94
	v_fmac_f32_e32 v31, v149, v95
	v_lshlrev_b32_e32 v151, 16, v171
	v_and_b32_e32 v153, 0xffff0000, v171
	v_fmac_f32_e32 v32, v151, v96
	v_fmac_f32_e32 v33, v153, v97
	v_lshlrev_b32_e32 v147, 16, v172
	v_and_b32_e32 v149, 0xffff0000, v172
	v_fmac_f32_e32 v34, v147, v98
	v_fmac_f32_e32 v35, v149, v99
	v_lshlrev_b32_e32 v151, 16, v173
	v_and_b32_e32 v153, 0xffff0000, v173
	v_fmac_f32_e32 v36, v151, v100
	v_fmac_f32_e32 v37, v153, v101
	v_lshlrev_b32_e32 v147, 16, v174
	v_and_b32_e32 v149, 0xffff0000, v174
	v_fmac_f32_e32 v38, v147, v102
	v_fmac_f32_e32 v39, v149, v103
	v_lshlrev_b32_e32 v151, 16, v175
	v_and_b32_e32 v153, 0xffff0000, v175
	v_fmac_f32_e32 v40, v151, v104
	v_fmac_f32_e32 v41, v153, v105
	v_lshlrev_b32_e32 v147, 16, v176
	v_and_b32_e32 v149, 0xffff0000, v176
	v_fmac_f32_e32 v42, v147, v106
	v_fmac_f32_e32 v43, v149, v107
	v_lshlrev_b32_e32 v151, 16, v177
	v_and_b32_e32 v153, 0xffff0000, v177
	v_fmac_f32_e32 v44, v151, v108
	v_fmac_f32_e32 v45, v153, v109
	v_lshlrev_b32_e32 v147, 16, v178
	v_and_b32_e32 v149, 0xffff0000, v178
	v_fmac_f32_e32 v46, v147, v110
	v_fmac_f32_e32 v47, v149, v111
	v_lshlrev_b32_e32 v151, 16, v179
	v_and_b32_e32 v153, 0xffff0000, v179
	v_fmac_f32_e32 v48, v151, v112
	v_fmac_f32_e32 v49, v153, v113
	v_lshlrev_b32_e32 v147, 16, v180
	v_and_b32_e32 v149, 0xffff0000, v180
	v_fmac_f32_e32 v50, v147, v114
	v_fmac_f32_e32 v51, v149, v115
	v_lshlrev_b32_e32 v151, 16, v181
	v_and_b32_e32 v153, 0xffff0000, v181
	v_fmac_f32_e32 v52, v151, v116
	v_fmac_f32_e32 v53, v153, v117
	v_lshlrev_b32_e32 v147, 16, v182
	v_and_b32_e32 v149, 0xffff0000, v182
	v_fmac_f32_e32 v54, v147, v118
	v_fmac_f32_e32 v55, v149, v119
	v_lshlrev_b32_e32 v151, 16, v183
	v_and_b32_e32 v153, 0xffff0000, v183
	v_fmac_f32_e32 v56, v151, v120
	v_fmac_f32_e32 v57, v153, v121
	v_lshlrev_b32_e32 v147, 16, v184
	v_and_b32_e32 v149, 0xffff0000, v184
	v_fmac_f32_e32 v58, v147, v122
	v_fmac_f32_e32 v59, v149, v123
	v_lshlrev_b32_e32 v151, 16, v185
	v_and_b32_e32 v153, 0xffff0000, v185
	v_fmac_f32_e32 v60, v151, v124
	v_fmac_f32_e32 v61, v153, v125
	v_lshlrev_b32_e32 v147, 16, v186
	v_and_b32_e32 v149, 0xffff0000, v186
	v_fmac_f32_e32 v62, v147, v126
	v_fmac_f32_e32 v63, v149, v127
	v_lshlrev_b32_e32 v151, 16, v187
	v_and_b32_e32 v153, 0xffff0000, v187
	v_fmac_f32_e32 v64, v151, v128
	v_fmac_f32_e32 v65, v153, v129
.Lmg_segnext:
	s_add_u32 s13, s13, 1
	s_cmp_lt_u32 s13, 8
	s_cbranch_scc1 .Lmg_seg
	s_sub_u32 s6, s2, s96
	s_subb_u32 s7, s3, s97
	s_add_u32 s6, s6, s90
	s_addc_u32 s7, s7, s91
	s_lshr_b32 s8, s19, 10
	s_add_u32 s6, s6, s8
	s_addc_u32 s7, s7, 0
	s_add_u32 s8, s6, 0x10000
	s_addc_u32 s9, s7, 0
	v_cvt_pk_bf16_f32 v224, v2, v3
	v_cvt_pk_bf16_f32 v225, v4, v5
	global_store_dwordx2 v146, v[224:225], s[6:7] offset:0
	v_cvt_pk_bf16_f32 v226, v6, v7
	v_cvt_pk_bf16_f32 v227, v8, v9
	global_store_dwordx2 v146, v[226:227], s[6:7] offset:16
	v_cvt_pk_bf16_f32 v228, v10, v11
	v_cvt_pk_bf16_f32 v229, v12, v13
	global_store_dwordx2 v146, v[228:229], s[6:7] offset:32
	v_cvt_pk_bf16_f32 v230, v14, v15
	v_cvt_pk_bf16_f32 v231, v16, v17
	global_store_dwordx2 v146, v[230:231], s[6:7] offset:48
	v_cvt_pk_bf16_f32 v224, v18, v19
	v_cvt_pk_bf16_f32 v225, v20, v21
	global_store_dwordx2 v146, v[224:225], s[6:7] offset:64
	v_cvt_pk_bf16_f32 v226, v22, v23
	v_cvt_pk_bf16_f32 v227, v24, v25
	global_store_dwordx2 v146, v[226:227], s[6:7] offset:80
	v_cvt_pk_bf16_f32 v228, v26, v27
	v_cvt_pk_bf16_f32 v229, v28, v29
	global_store_dwordx2 v146, v[228:229], s[6:7] offset:96
	v_cvt_pk_bf16_f32 v230, v30, v31
	v_cvt_pk_bf16_f32 v231, v32, v33
	global_store_dwordx2 v146, v[230:231], s[6:7] offset:112
	v_cvt_pk_bf16_f32 v224, v34, v35
	v_cvt_pk_bf16_f32 v225, v36, v37
	global_store_dwordx2 v146, v[224:225], s[8:9] offset:0
	v_cvt_pk_bf16_f32 v226, v38, v39
	v_cvt_pk_bf16_f32 v227, v40, v41
	global_store_dwordx2 v146, v[226:227], s[8:9] offset:16
	v_cvt_pk_bf16_f32 v228, v42, v43
	v_cvt_pk_bf16_f32 v229, v44, v45
	global_store_dwordx2 v146, v[228:229], s[8:9] offset:32
	v_cvt_pk_bf16_f32 v230, v46, v47
	v_cvt_pk_bf16_f32 v231, v48, v49
	global_store_dwordx2 v146, v[230:231], s[8:9] offset:48
	v_cvt_pk_bf16_f32 v224, v50, v51
	v_cvt_pk_bf16_f32 v225, v52, v53
	global_store_dwordx2 v146, v[224:225], s[8:9] offset:64
	v_cvt_pk_bf16_f32 v226, v54, v55
	v_cvt_pk_bf16_f32 v227, v56, v57
	global_store_dwordx2 v146, v[226:227], s[8:9] offset:80
	v_cvt_pk_bf16_f32 v228, v58, v59
	v_cvt_pk_bf16_f32 v229, v60, v61
	global_store_dwordx2 v146, v[228:229], s[8:9] offset:96
	v_cvt_pk_bf16_f32 v230, v62, v63
	v_cvt_pk_bf16_f32 v231, v64, v65
	global_store_dwordx2 v146, v[230:231], s[8:9] offset:112
	s_cmp_eq_u32 s18, 0
	s_cbranch_scc1 .Lmg_item
	s_add_u32 s12, s12, s49
	s_branch .Lmg_item
.Lmg_done:
	s_waitcnt vmcnt(0) lgkmcnt(0)
